# mem_qblock (prompt) QK section regenerated as 3-deep software pipeline (K frags prefetched 2 key-blocks ahead)
# speedup vs baseline: 1.0043x; 1.0043x over previous
.LBB0_1059:
	v_lshl_add_u64 v[34:35], s[22:23], 0, v[20:21]
	global_load_dwordx4 v[4:7], v[34:35], off offset:-128 nt
	global_load_dwordx4 v[0:3], v[34:35], off offset:-64 nt
	global_load_dwordx4 v[8:11], v[34:35], off nt
	v_lshl_add_u64 v[36:37], s[22:23], 0, v[16:17]
	v_add_co_u32_e32 v38, vcc, 0x18fc4000, v36
	s_nop 1
	v_addc_co_u32_e32 v39, vcc, 0, v37, vcc
	v_add_co_u32_e32 v36, vcc, 0x18fe5000, v36
	s_nop 1
	v_addc_co_u32_e32 v37, vcc, 0, v37, vcc
	global_load_dword v38, v[38:39], off
	global_load_dword v39, v[36:37], off
	global_load_dwordx4 v[12:15], v[34:35], off offset:64 nt
	ds_read_b128 v[160:163], v123
	ds_read_b128 v[164:167], v123 offset:64
	ds_read_b128 v[168:171], v123 offset:128
	ds_read_b128 v[172:175], v123 offset:192
	ds_read_b128 v[176:179], v123 offset:4352
	ds_read_b128 v[180:183], v123 offset:4416
	ds_read_b128 v[184:187], v123 offset:4480
	ds_read_b128 v[188:191], v123 offset:4544
	s_waitcnt vmcnt(0)
	v_add_f32_e32 v38, v38, v39
	v_fmamk_f32 v38, v38, 0x3c000000, v136
	v_rsq_f32_e32 v34, v38
	s_nop 0
	v_mul_f32_e32 v40, 0x3e0293ee, v34
	ds_read_b128 v[204:207], v123 offset:8704
	ds_read_b128 v[208:211], v123 offset:8768
	ds_read_b128 v[212:215], v123 offset:8832
	ds_read_b128 v[216:219], v123 offset:8896
	s_waitcnt lgkmcnt(8)
	v_mfma_f32_16x16x32_bf16 v[224:227], v[160:163], v[4:7], 0
	v_mfma_f32_16x16x32_bf16 v[224:227], v[164:167], v[0:3], v[224:227]
	v_mfma_f32_16x16x32_bf16 v[224:227], v[168:171], v[8:11], v[224:227]
	v_mfma_f32_16x16x32_bf16 v[224:227], v[172:175], v[12:15], v[224:227]
	ds_read_b128 v[160:163], v123 offset:13056
	ds_read_b128 v[164:167], v123 offset:13120
	ds_read_b128 v[168:171], v123 offset:13184
	ds_read_b128 v[172:175], v123 offset:13248
	s_waitcnt lgkmcnt(8)
	v_mfma_f32_16x16x32_bf16 v[228:231], v[176:179], v[4:7], 0
	v_mfma_f32_16x16x32_bf16 v[228:231], v[180:183], v[0:3], v[228:231]
	v_mfma_f32_16x16x32_bf16 v[228:231], v[184:187], v[8:11], v[228:231]
	v_mfma_f32_16x16x32_bf16 v[228:231], v[188:191], v[12:15], v[228:231]
	s_nop 3
	v_mul_f32_e32 v36, v40, v224
	v_mul_f32_e32 v37, v40, v225
	v_mul_f32_e32 v28, v40, v226
	v_mul_f32_e32 v29, v40, v227
	ds_read_b128 v[176:179], v123 offset:17408
	ds_read_b128 v[180:183], v123 offset:17472
	ds_read_b128 v[184:187], v123 offset:17536
	ds_read_b128 v[188:191], v123 offset:17600
	s_waitcnt lgkmcnt(8)
	v_mfma_f32_16x16x32_bf16 v[224:227], v[204:207], v[4:7], 0
	v_mfma_f32_16x16x32_bf16 v[224:227], v[208:211], v[0:3], v[224:227]
	v_mfma_f32_16x16x32_bf16 v[224:227], v[212:215], v[8:11], v[224:227]
	v_mfma_f32_16x16x32_bf16 v[224:227], v[216:219], v[12:15], v[224:227]
	s_nop 3
	v_mul_f32_e32 v26, v40, v228
	v_mul_f32_e32 v27, v40, v229
	v_mul_f32_e32 v22, v40, v230
	v_mul_f32_e32 v23, v40, v231
	ds_read_b128 v[204:207], v123 offset:21760
	ds_read_b128 v[208:211], v123 offset:21824
	ds_read_b128 v[212:215], v123 offset:21888
	ds_read_b128 v[216:219], v123 offset:21952
	s_waitcnt lgkmcnt(8)
	v_mfma_f32_16x16x32_bf16 v[228:231], v[160:163], v[4:7], 0
	v_mfma_f32_16x16x32_bf16 v[228:231], v[164:167], v[0:3], v[228:231]
	v_mfma_f32_16x16x32_bf16 v[228:231], v[168:171], v[8:11], v[228:231]
	v_mfma_f32_16x16x32_bf16 v[228:231], v[172:175], v[12:15], v[228:231]
	s_nop 3
	v_mul_f32_e32 v58, v40, v224
	v_mul_f32_e32 v59, v40, v225
	v_mul_f32_e32 v34, v40, v226
	v_mul_f32_e32 v35, v40, v227
	ds_read_b128 v[160:163], v123 offset:26112
	ds_read_b128 v[164:167], v123 offset:26176
	ds_read_b128 v[168:171], v123 offset:26240
	ds_read_b128 v[172:175], v123 offset:26304
	s_waitcnt lgkmcnt(8)
	v_mfma_f32_16x16x32_bf16 v[224:227], v[176:179], v[4:7], 0
	v_mfma_f32_16x16x32_bf16 v[224:227], v[180:183], v[0:3], v[224:227]
	v_mfma_f32_16x16x32_bf16 v[224:227], v[184:187], v[8:11], v[224:227]
	v_mfma_f32_16x16x32_bf16 v[224:227], v[188:191], v[12:15], v[224:227]
	s_nop 3
	v_mul_f32_e32 v32, v40, v228
	v_mul_f32_e32 v33, v40, v229
	v_mul_f32_e32 v24, v40, v230
	v_mul_f32_e32 v25, v40, v231
	ds_read_b128 v[176:179], v123 offset:30464
	ds_read_b128 v[180:183], v123 offset:30528
	ds_read_b128 v[184:187], v123 offset:30592
	ds_read_b128 v[188:191], v123 offset:30656
	s_waitcnt lgkmcnt(8)
	v_mfma_f32_16x16x32_bf16 v[228:231], v[204:207], v[4:7], 0
	v_mfma_f32_16x16x32_bf16 v[228:231], v[208:211], v[0:3], v[228:231]
	v_mfma_f32_16x16x32_bf16 v[228:231], v[212:215], v[8:11], v[228:231]
	v_mfma_f32_16x16x32_bf16 v[228:231], v[216:219], v[12:15], v[228:231]
	s_nop 3
	v_mul_f32_e32 v62, v40, v224
	v_mul_f32_e32 v63, v40, v225
	v_mul_f32_e32 v56, v40, v226
	v_mul_f32_e32 v57, v40, v227
	ds_read_b128 v[204:207], v123 offset:34816
	ds_read_b128 v[208:211], v123 offset:34880
	ds_read_b128 v[212:215], v123 offset:34944
	ds_read_b128 v[216:219], v123 offset:35008
	s_waitcnt lgkmcnt(8)
	v_mfma_f32_16x16x32_bf16 v[224:227], v[160:163], v[4:7], 0
	v_mfma_f32_16x16x32_bf16 v[224:227], v[164:167], v[0:3], v[224:227]
	v_mfma_f32_16x16x32_bf16 v[224:227], v[168:171], v[8:11], v[224:227]
	v_mfma_f32_16x16x32_bf16 v[224:227], v[172:175], v[12:15], v[224:227]
	s_nop 3
	v_mul_f32_e32 v54, v40, v228
	v_mul_f32_e32 v55, v40, v229
	v_mul_f32_e32 v30, v40, v230
	v_mul_f32_e32 v31, v40, v231
	ds_read_b128 v[160:163], v123 offset:39168
	ds_read_b128 v[164:167], v123 offset:39232
	ds_read_b128 v[168:171], v123 offset:39296
	ds_read_b128 v[172:175], v123 offset:39360
	s_waitcnt lgkmcnt(8)
	v_mfma_f32_16x16x32_bf16 v[228:231], v[176:179], v[4:7], 0
	v_mfma_f32_16x16x32_bf16 v[228:231], v[180:183], v[0:3], v[228:231]
	v_mfma_f32_16x16x32_bf16 v[228:231], v[184:187], v[8:11], v[228:231]
	v_mfma_f32_16x16x32_bf16 v[228:231], v[188:191], v[12:15], v[228:231]
	s_nop 3
	v_mul_f32_e32 v86, v40, v224
	v_mul_f32_e32 v87, v40, v225
	v_mul_f32_e32 v74, v40, v226
	v_mul_f32_e32 v75, v40, v227
	ds_read_b128 v[176:179], v123 offset:43520
	ds_read_b128 v[180:183], v123 offset:43584
	ds_read_b128 v[184:187], v123 offset:43648
	ds_read_b128 v[188:191], v123 offset:43712
	s_waitcnt lgkmcnt(8)
	v_mfma_f32_16x16x32_bf16 v[224:227], v[204:207], v[4:7], 0
	v_mfma_f32_16x16x32_bf16 v[224:227], v[208:211], v[0:3], v[224:227]
	v_mfma_f32_16x16x32_bf16 v[224:227], v[212:215], v[8:11], v[224:227]
	v_mfma_f32_16x16x32_bf16 v[224:227], v[216:219], v[12:15], v[224:227]
	s_nop 3
	v_mul_f32_e32 v60, v40, v228
	v_mul_f32_e32 v61, v40, v229
	v_mul_f32_e32 v38, v40, v230
	v_mul_f32_e32 v39, v40, v231
	ds_read_b128 v[204:207], v123 offset:47872
	ds_read_b128 v[208:211], v123 offset:47936
	ds_read_b128 v[212:215], v123 offset:48000
	ds_read_b128 v[216:219], v123 offset:48064
	s_waitcnt lgkmcnt(8)
	v_mfma_f32_16x16x32_bf16 v[228:231], v[160:163], v[4:7], 0
	v_mfma_f32_16x16x32_bf16 v[228:231], v[164:167], v[0:3], v[228:231]
	v_mfma_f32_16x16x32_bf16 v[228:231], v[168:171], v[8:11], v[228:231]
	v_mfma_f32_16x16x32_bf16 v[228:231], v[172:175], v[12:15], v[228:231]
	s_nop 3
	v_mul_f32_e32 v94, v40, v224
	v_mul_f32_e32 v95, v40, v225
	v_mul_f32_e32 v84, v40, v226
	v_mul_f32_e32 v85, v40, v227
	ds_read_b128 v[160:163], v123 offset:52224
	ds_read_b128 v[164:167], v123 offset:52288
	ds_read_b128 v[168:171], v123 offset:52352
	ds_read_b128 v[172:175], v123 offset:52416
	s_waitcnt lgkmcnt(8)
	v_mfma_f32_16x16x32_bf16 v[224:227], v[176:179], v[4:7], 0
	v_mfma_f32_16x16x32_bf16 v[224:227], v[180:183], v[0:3], v[224:227]
	v_mfma_f32_16x16x32_bf16 v[224:227], v[184:187], v[8:11], v[224:227]
	v_mfma_f32_16x16x32_bf16 v[224:227], v[188:191], v[12:15], v[224:227]
	s_nop 3
	v_mul_f32_e32 v78, v40, v228
	v_mul_f32_e32 v79, v40, v229
	v_mul_f32_e32 v72, v40, v230
	v_mul_f32_e32 v73, v40, v231
	ds_read_b128 v[176:179], v123 offset:56576
	ds_read_b128 v[180:183], v123 offset:56640
	ds_read_b128 v[184:187], v123 offset:56704
	ds_read_b128 v[188:191], v123 offset:56768
	s_waitcnt lgkmcnt(8)
	v_mfma_f32_16x16x32_bf16 v[228:231], v[204:207], v[4:7], 0
	v_mfma_f32_16x16x32_bf16 v[228:231], v[208:211], v[0:3], v[228:231]
	v_mfma_f32_16x16x32_bf16 v[228:231], v[212:215], v[8:11], v[228:231]
	v_mfma_f32_16x16x32_bf16 v[228:231], v[216:219], v[12:15], v[228:231]
	s_nop 3
	v_mul_f32_e32 v102, v40, v224
	v_mul_f32_e32 v103, v40, v225
	v_mul_f32_e32 v92, v40, v226
	v_mul_f32_e32 v93, v40, v227
	ds_read_b128 v[204:207], v123 offset:60928
	ds_read_b128 v[208:211], v123 offset:60992
	ds_read_b128 v[212:215], v123 offset:61056
	ds_read_b128 v[216:219], v123 offset:61120
	s_waitcnt lgkmcnt(8)
	v_mfma_f32_16x16x32_bf16 v[224:227], v[160:163], v[4:7], 0
	v_mfma_f32_16x16x32_bf16 v[224:227], v[164:167], v[0:3], v[224:227]
	v_mfma_f32_16x16x32_bf16 v[224:227], v[168:171], v[8:11], v[224:227]
	v_mfma_f32_16x16x32_bf16 v[224:227], v[172:175], v[12:15], v[224:227]
	s_nop 3
	v_mul_f32_e32 v90, v40, v228
	v_mul_f32_e32 v91, v40, v229
	v_mul_f32_e32 v76, v40, v230
	v_mul_f32_e32 v77, v40, v231
	ds_read_b128 v[160:163], v123 offset:65280
	ds_read_b128 v[164:167], v123 offset:65344
	ds_read_b128 v[168:171], v123 offset:65408
	ds_read_b128 v[172:175], v123 offset:65472
	s_waitcnt lgkmcnt(8)
	v_mfma_f32_16x16x32_bf16 v[228:231], v[176:179], v[4:7], 0
	v_mfma_f32_16x16x32_bf16 v[228:231], v[180:183], v[0:3], v[228:231]
	v_mfma_f32_16x16x32_bf16 v[228:231], v[184:187], v[8:11], v[228:231]
	v_mfma_f32_16x16x32_bf16 v[228:231], v[188:191], v[12:15], v[228:231]
	s_nop 3
	v_mul_f32_e32 v104, v40, v224
	v_mul_f32_e32 v105, v40, v225
	v_mul_f32_e32 v100, v40, v226
	v_mul_f32_e32 v101, v40, v227
	s_waitcnt lgkmcnt(4)
	v_mfma_f32_16x16x32_bf16 v[224:227], v[204:207], v[4:7], 0
	v_mfma_f32_16x16x32_bf16 v[224:227], v[208:211], v[0:3], v[224:227]
	v_mfma_f32_16x16x32_bf16 v[224:227], v[212:215], v[8:11], v[224:227]
	v_mfma_f32_16x16x32_bf16 v[224:227], v[216:219], v[12:15], v[224:227]
	s_nop 3
	v_mul_f32_e32 v98, v40, v228
	v_mul_f32_e32 v99, v40, v229
	v_mul_f32_e32 v88, v40, v230
	v_mul_f32_e32 v89, v40, v231
	s_waitcnt lgkmcnt(0)
	v_mfma_f32_16x16x32_bf16 v[228:231], v[160:163], v[4:7], 0
	v_mfma_f32_16x16x32_bf16 v[228:231], v[164:167], v[0:3], v[228:231]
	v_mfma_f32_16x16x32_bf16 v[228:231], v[168:171], v[8:11], v[228:231]
	v_mfma_f32_16x16x32_bf16 v[228:231], v[172:175], v[12:15], v[228:231]
	s_nop 3
	v_mul_f32_e32 v0, v40, v224
	v_mul_f32_e32 v1, v40, v225
	v_mul_f32_e32 v4, v40, v226
	v_mul_f32_e32 v5, v40, v227
	s_nop 7
	v_mul_f32_e32 v2, v40, v228
	v_mul_f32_e32 v3, v40, v229
	v_mul_f32_e32 v6, v40, v230
	v_mul_f32_e32 v7, v40, v231
	v_max_f32_e32 v8, v36, v37
	v_max_f32_e32 v9, v28, v29
	v_max3_f32 v8, v8, s30, v9
	v_max_f32_e32 v9, v26, v27
	v_max_f32_e32 v10, v22, v23
	v_max3_f32 v8, v8, v9, v10
	v_max_f32_e32 v9, v58, v59
	v_max_f32_e32 v10, v34, v35
	v_max3_f32 v8, v8, v9, v10
	v_max_f32_e32 v9, v32, v33
	v_max_f32_e32 v10, v24, v25
	v_max3_f32 v8, v8, v9, v10
	v_max_f32_e32 v9, v62, v63
	v_max_f32_e32 v10, v56, v57
	v_max3_f32 v8, v8, v9, v10
	v_max_f32_e32 v9, v54, v55
	v_max_f32_e32 v10, v30, v31
	v_max3_f32 v8, v8, v9, v10
	v_max_f32_e32 v9, v86, v87
	v_max_f32_e32 v10, v74, v75
	v_max3_f32 v8, v8, v9, v10
	v_max_f32_e32 v9, v60, v61
	v_max_f32_e32 v10, v38, v39
	v_max3_f32 v8, v8, v9, v10
	v_max_f32_e32 v9, v94, v95
	v_max_f32_e32 v10, v84, v85
	v_max3_f32 v8, v8, v9, v10
	v_max_f32_e32 v9, v78, v79
	v_max_f32_e32 v10, v72, v73
	v_max3_f32 v8, v8, v9, v10
	v_max_f32_e32 v9, v102, v103
	v_max_f32_e32 v10, v92, v93
	v_max3_f32 v8, v8, v9, v10
	v_max_f32_e32 v9, v90, v91
	v_max_f32_e32 v10, v76, v77
	v_max3_f32 v8, v8, v9, v10
	v_max_f32_e32 v9, v104, v105
	v_max_f32_e32 v10, v100, v101
	v_max3_f32 v8, v8, v9, v10
	v_max_f32_e32 v9, v98, v99
	v_max_f32_e32 v10, v88, v89
	v_max3_f32 v8, v8, v9, v10
	v_max_f32_e32 v9, v0, v1
	v_max_f32_e32 v10, v4, v5
	v_max3_f32 v8, v8, v9, v10
	v_max_f32_e32 v9, v2, v3
	v_max_f32_e32 v10, v6, v7
	v_max3_f32 v8, v8, v9, v10
	ds_bpermute_b32 v9, v51, v8
	s_waitcnt lgkmcnt(0)
	v_max_f32_e32 v9, v9, v9
	v_max_f32_e32 v8, v8, v9
	ds_bpermute_b32 v9, v53, v8
	s_waitcnt lgkmcnt(0)
	v_max_f32_e32 v9, v9, v9
	v_max_f32_e32 v8, v8, v9
	v_sub_f32_e32 v9, v36, v8
	v_exp_f32_e32 v140, v9
	v_sub_f32_e32 v9, v37, v8
	v_exp_f32_e32 v141, v9
	v_sub_f32_e32 v9, v28, v8
	v_exp_f32_e32 v142, v9
	v_sub_f32_e32 v9, v29, v8
	v_exp_f32_e32 v143, v9
	v_sub_f32_e32 v10, v26, v8
	v_add_f32_e32 v9, 0, v140
	v_exp_f32_e32 v144, v10
	v_sub_f32_e32 v10, v27, v8
	v_add_f32_e32 v9, v141, v9
	v_exp_f32_e32 v145, v10
	v_sub_f32_e32 v10, v22, v8
	v_add_f32_e32 v9, v142, v9
	v_exp_f32_e32 v146, v10
	v_sub_f32_e32 v10, v23, v8
	v_add_f32_e32 v9, v143, v9
	v_exp_f32_e32 v147, v10
	v_sub_f32_e32 v10, v58, v8
	v_add_f32_e32 v9, v144, v9
	v_exp_f32_e32 v70, v10
	v_sub_f32_e32 v10, v59, v8
	v_add_f32_e32 v9, v145, v9
	v_exp_f32_e32 v71, v10
	v_sub_f32_e32 v10, v34, v8
	v_add_f32_e32 v9, v146, v9
	v_exp_f32_e32 v82, v10
	v_sub_f32_e32 v10, v35, v8
	v_add_f32_e32 v9, v147, v9
	v_exp_f32_e32 v83, v10
	v_sub_f32_e32 v10, v32, v8
	v_add_f32_e32 v9, v70, v9
	v_exp_f32_e32 v80, v10
	v_sub_f32_e32 v10, v33, v8
	v_add_f32_e32 v9, v71, v9
	v_exp_f32_e32 v81, v10
	v_sub_f32_e32 v10, v24, v8
	v_add_f32_e32 v9, v82, v9
	v_exp_f32_e32 v96, v10
	v_sub_f32_e32 v10, v25, v8
	v_add_f32_e32 v9, v83, v9
	v_exp_f32_e32 v97, v10
	v_sub_f32_e32 v10, v62, v8
	v_add_f32_e32 v9, v80, v9
	v_exp_f32_e32 v62, v10
	v_sub_f32_e32 v10, v63, v8
	v_add_f32_e32 v9, v81, v9
	v_exp_f32_e32 v63, v10
	v_sub_f32_e32 v10, v56, v8
	v_add_f32_e32 v9, v96, v9
	v_exp_f32_e32 v66, v10
	v_sub_f32_e32 v10, v57, v8
	v_add_f32_e32 v9, v97, v9
	v_exp_f32_e32 v67, v10
	v_sub_f32_e32 v10, v54, v8
	v_add_f32_e32 v9, v62, v9
	v_exp_f32_e32 v64, v10
	v_sub_f32_e32 v10, v55, v8
	v_add_f32_e32 v9, v63, v9
	v_exp_f32_e32 v65, v10
	v_sub_f32_e32 v10, v30, v8
	v_add_f32_e32 v9, v66, v9
	v_exp_f32_e32 v68, v10
	v_sub_f32_e32 v10, v31, v8
	v_add_f32_e32 v9, v67, v9
	v_exp_f32_e32 v69, v10
	v_sub_f32_e32 v10, v86, v8
	v_add_f32_e32 v9, v64, v9
	v_exp_f32_e32 v54, v10
	v_sub_f32_e32 v10, v87, v8
	v_add_f32_e32 v9, v65, v9
	v_exp_f32_e32 v55, v10
	v_sub_f32_e32 v10, v74, v8
	v_add_f32_e32 v9, v68, v9
	v_exp_f32_e32 v58, v10
	v_sub_f32_e32 v10, v75, v8
	v_add_f32_e32 v9, v69, v9
	v_exp_f32_e32 v59, v10
	v_sub_f32_e32 v10, v60, v8
	v_add_f32_e32 v9, v54, v9
	v_exp_f32_e32 v56, v10
	v_sub_f32_e32 v10, v61, v8
	v_add_f32_e32 v9, v55, v9
	v_exp_f32_e32 v57, v10
	v_sub_f32_e32 v10, v38, v8
	v_add_f32_e32 v9, v58, v9
	v_exp_f32_e32 v60, v10
	v_sub_f32_e32 v10, v39, v8
	v_add_f32_e32 v9, v59, v9
	v_exp_f32_e32 v61, v10
	v_sub_f32_e32 v10, v94, v8
	v_add_f32_e32 v9, v56, v9
	v_exp_f32_e32 v32, v10
	v_sub_f32_e32 v10, v95, v8
	v_add_f32_e32 v9, v57, v9
	v_exp_f32_e32 v33, v10
	v_sub_f32_e32 v10, v84, v8
	v_add_f32_e32 v9, v60, v9
	v_exp_f32_e32 v36, v10
	v_sub_f32_e32 v10, v85, v8
	v_add_f32_e32 v9, v61, v9
	v_exp_f32_e32 v37, v10
	v_sub_f32_e32 v10, v78, v8
	v_add_f32_e32 v9, v32, v9
	v_exp_f32_e32 v34, v10
	v_sub_f32_e32 v10, v79, v8
	v_add_f32_e32 v9, v33, v9
	v_exp_f32_e32 v35, v10
	v_sub_f32_e32 v10, v72, v8
	v_add_f32_e32 v9, v36, v9
	v_exp_f32_e32 v38, v10
	v_sub_f32_e32 v10, v73, v8
	v_add_f32_e32 v9, v37, v9
	v_exp_f32_e32 v39, v10
	v_sub_f32_e32 v10, v102, v8
	v_add_f32_e32 v9, v34, v9
	v_exp_f32_e32 v24, v10
	v_sub_f32_e32 v10, v103, v8
	v_add_f32_e32 v9, v35, v9
	v_exp_f32_e32 v25, v10
	v_sub_f32_e32 v10, v92, v8
	v_add_f32_e32 v9, v38, v9
	v_exp_f32_e32 v28, v10
	v_sub_f32_e32 v10, v93, v8
	v_add_f32_e32 v9, v39, v9
	v_exp_f32_e32 v29, v10
	v_sub_f32_e32 v10, v90, v8
	v_add_f32_e32 v9, v24, v9
	v_exp_f32_e32 v26, v10
	v_sub_f32_e32 v10, v91, v8
	v_add_f32_e32 v9, v25, v9
	v_exp_f32_e32 v27, v10
	v_sub_f32_e32 v10, v76, v8
	v_add_f32_e32 v9, v28, v9
	v_exp_f32_e32 v30, v10
	v_sub_f32_e32 v10, v77, v8
	v_add_f32_e32 v9, v29, v9
	v_exp_f32_e32 v31, v10
	v_sub_f32_e32 v10, v104, v8
	v_add_f32_e32 v9, v26, v9
	v_exp_f32_e32 v10, v10
	v_sub_f32_e32 v11, v105, v8
	v_add_f32_e32 v9, v27, v9
	v_exp_f32_e32 v11, v11
	v_sub_f32_e32 v12, v100, v8
	v_add_f32_e32 v9, v30, v9
	v_exp_f32_e32 v14, v12
	v_sub_f32_e32 v12, v101, v8
	v_add_f32_e32 v9, v31, v9
	v_exp_f32_e32 v15, v12
	v_sub_f32_e32 v12, v98, v8
	v_add_f32_e32 v9, v10, v9
	v_exp_f32_e32 v12, v12
	v_sub_f32_e32 v13, v99, v8
	v_add_f32_e32 v9, v11, v9
	v_exp_f32_e32 v13, v13
	v_sub_f32_e32 v22, v88, v8
	v_add_f32_e32 v9, v14, v9
	v_exp_f32_e32 v22, v22
	v_sub_f32_e32 v23, v89, v8
	v_add_f32_e32 v9, v15, v9
	v_exp_f32_e32 v23, v23
	v_sub_f32_e32 v0, v0, v8
	v_add_f32_e32 v9, v12, v9
	v_exp_f32_e32 v0, v0
	v_sub_f32_e32 v1, v1, v8
	v_add_f32_e32 v9, v13, v9
	v_exp_f32_e32 v1, v1
	v_sub_f32_e32 v4, v4, v8
	v_add_f32_e32 v9, v22, v9
	v_exp_f32_e32 v4, v4
	v_sub_f32_e32 v5, v5, v8
	v_add_f32_e32 v9, v23, v9
	v_exp_f32_e32 v5, v5
	v_sub_f32_e32 v2, v2, v8
	v_add_f32_e32 v9, v0, v9
	v_exp_f32_e32 v2, v2
	v_sub_f32_e32 v3, v3, v8
	v_add_f32_e32 v9, v1, v9
	v_exp_f32_e32 v3, v3
	v_sub_f32_e32 v6, v6, v8
	v_add_f32_e32 v9, v4, v9
	v_exp_f32_e32 v6, v6
	v_sub_f32_e32 v7, v7, v8
	v_add_f32_e32 v9, v5, v9
	v_exp_f32_e32 v7, v7
	v_add_f32_e32 v8, v2, v9
	v_add_f32_e32 v8, v3, v8
	v_add_f32_e32 v8, v6, v8
	v_add_f32_e32 v8, v7, v8
	ds_bpermute_b32 v9, v51, v8
	ds_read_b64_tr_b16 v[78:79], v133 offset:4352
	ds_read_b64_tr_b16 v[76:77], v133
	s_waitcnt lgkmcnt(2)
	v_add_f32_e32 v8, v8, v9
	ds_bpermute_b32 v9, v53, v8
	s_waitcnt lgkmcnt(0)
	v_add_f32_e32 v8, v8, v9
	v_rcp_f32_e32 v8, v8
	s_nop 0
	v_pk_mul_f32 v[74:75], v[142:143], v[8:9] op_sel_hi:[1,0]
	v_pk_mul_f32 v[72:73], v[140:141], v[8:9] op_sel_hi:[1,0]
	v_pk_mul_f32 v[84:85], v[146:147], v[8:9] op_sel_hi:[1,0]
	v_pk_mul_f32 v[86:87], v[144:145], v[8:9] op_sel_hi:[1,0]
	v_cvt_pk_bf16_f32 v72, v72, v73
	v_cvt_pk_bf16_f32 v73, v74, v75
	v_cvt_pk_bf16_f32 v74, v86, v87
	v_cvt_pk_bf16_f32 v75, v84, v85
	ds_read_b64_tr_b16 v[86:87], v133 offset:4384
	ds_read_b64_tr_b16 v[84:85], v133 offset:32
	ds_read_b64_tr_b16 v[88:89], v133 offset:64
	ds_read_b64_tr_b16 v[92:93], v133 offset:96
	ds_read_b64_tr_b16 v[90:91], v133 offset:4416
	ds_read_b64_tr_b16 v[94:95], v133 offset:4448
	ds_read_b64_tr_b16 v[98:99], v133 offset:128
	ds_read_b64_tr_b16 v[100:101], v133 offset:4480
	ds_read_b64_tr_b16 v[104:105], v133 offset:4512
	ds_read_b64_tr_b16 v[102:103], v133 offset:160
	ds_read_b64_tr_b16 v[140:141], v133 offset:192
	ds_read_b64_tr_b16 v[144:145], v133 offset:224
	ds_read_b64_tr_b16 v[142:143], v133 offset:4544
	ds_read_b64_tr_b16 v[146:147], v133 offset:4576
	v_mfma_f32_16x16x32_bf16 v[76:79], v[76:79], v[72:75], 0
	s_waitcnt lgkmcnt(12)
	v_mfma_f32_16x16x32_bf16 v[84:87], v[84:87], v[72:75], 0
	s_waitcnt lgkmcnt(9)
	v_mfma_f32_16x16x32_bf16 v[88:91], v[88:91], v[72:75], 0
	s_waitcnt lgkmcnt(8)
	v_mfma_f32_16x16x32_bf16 v[92:95], v[92:95], v[72:75], 0
	s_waitcnt lgkmcnt(6)
	v_mfma_f32_16x16x32_bf16 v[98:101], v[98:101], v[72:75], 0
	s_waitcnt lgkmcnt(4)
	v_mfma_f32_16x16x32_bf16 v[102:105], v[102:105], v[72:75], 0
	s_waitcnt lgkmcnt(1)
	v_mfma_f32_16x16x32_bf16 v[140:143], v[140:143], v[72:75], 0
	s_waitcnt lgkmcnt(0)
	v_mfma_f32_16x16x32_bf16 v[72:75], v[144:147], v[72:75], 0
	v_mul_f32_e64 v82, v82, v8
	v_mul_f32_e64 v83, v83, v8
	v_pk_mul_f32 v[148:149], v[80:81], v[8:9] op_sel_hi:[1,0]
	v_cvt_pk_bf16_f32 v81, v82, v83
	ds_read_b64_tr_b16 v[146:147], v133 offset:13056
	ds_read_b64_tr_b16 v[144:145], v133 offset:8704
	v_cvt_pk_bf16_f32 v82, v148, v149
	ds_read_b64_tr_b16 v[150:151], v133 offset:13088
	ds_read_b64_tr_b16 v[148:149], v133 offset:8736
	ds_read_b64_tr_b16 v[152:153], v133 offset:8768
	ds_read_b64_tr_b16 v[156:157], v133 offset:8800
	ds_read_b64_tr_b16 v[154:155], v133 offset:13120
	ds_read_b64_tr_b16 v[158:159], v133 offset:13152
	v_pk_mul_f32 v[70:71], v[70:71], v[8:9] op_sel_hi:[1,0]
	v_pk_mul_f32 v[96:97], v[96:97], v[8:9] op_sel_hi:[1,0]
	v_cvt_pk_bf16_f32 v80, v70, v71
	v_cvt_pk_bf16_f32 v83, v96, v97
	s_waitcnt lgkmcnt(6)
	s_nop 0
	v_mfma_f32_16x16x32_bf16 v[76:79], v[144:147], v[80:83], v[76:79]
	ds_read_b64_tr_b16 v[144:145], v133 offset:8832
	ds_read_b64_tr_b16 v[146:147], v133 offset:13184
	s_waitcnt lgkmcnt(6)
	v_mfma_f32_16x16x32_bf16 v[84:87], v[148:151], v[80:83], v[84:87]
	s_waitcnt lgkmcnt(3)
	v_mfma_f32_16x16x32_bf16 v[88:91], v[152:155], v[80:83], v[88:91]
	s_waitcnt lgkmcnt(2)
	v_mfma_f32_16x16x32_bf16 v[92:95], v[156:159], v[80:83], v[92:95]
	ds_read_b64_tr_b16 v[150:151], v133 offset:13216
	ds_read_b64_tr_b16 v[148:149], v133 offset:8864
	ds_read_b64_tr_b16 v[152:153], v133 offset:8896
	ds_read_b64_tr_b16 v[156:157], v133 offset:8928
	ds_read_b64_tr_b16 v[154:155], v133 offset:13248
	ds_read_b64_tr_b16 v[158:159], v133 offset:13280
	s_waitcnt lgkmcnt(6)
	v_mfma_f32_16x16x32_bf16 v[96:99], v[144:147], v[80:83], v[98:101]
	s_waitcnt lgkmcnt(4)
	v_mfma_f32_16x16x32_bf16 v[100:103], v[148:151], v[80:83], v[102:105]
	s_waitcnt lgkmcnt(1)
	v_mfma_f32_16x16x32_bf16 v[140:143], v[152:155], v[80:83], v[140:143]
	s_waitcnt lgkmcnt(0)
	v_mfma_f32_16x16x32_bf16 v[70:73], v[156:159], v[80:83], v[72:75]
	v_mul_f32_e64 v66, v66, v8
	v_mul_f32_e64 v67, v67, v8
	v_pk_mul_f32 v[62:63], v[62:63], v[8:9] op_sel_hi:[1,0]
	v_pk_mul_f32 v[74:75], v[68:69], v[8:9] op_sel_hi:[1,0]
	v_cvt_pk_bf16_f32 v62, v62, v63
	v_cvt_pk_bf16_f32 v63, v66, v67
	ds_read_b64_tr_b16 v[68:69], v133 offset:21760
	ds_read_b64_tr_b16 v[66:67], v133 offset:17408
	ds_read_b64_tr_b16 v[82:83], v133 offset:21792
	ds_read_b64_tr_b16 v[80:81], v133 offset:17440
	ds_read_b64_tr_b16 v[144:145], v133 offset:17472
	ds_read_b64_tr_b16 v[148:149], v133 offset:17504
	ds_read_b64_tr_b16 v[146:147], v133 offset:21824
	ds_read_b64_tr_b16 v[150:151], v133 offset:21856
	v_pk_mul_f32 v[64:65], v[64:65], v[8:9] op_sel_hi:[1,0]
	s_nop 0
	v_cvt_pk_bf16_f32 v64, v64, v65
	v_cvt_pk_bf16_f32 v65, v74, v75
	s_waitcnt lgkmcnt(6)
	s_nop 0
	v_mfma_f32_16x16x32_bf16 v[66:69], v[66:69], v[62:65], v[76:79]
	s_waitcnt lgkmcnt(4)
	v_mfma_f32_16x16x32_bf16 v[74:77], v[80:83], v[62:65], v[84:87]
	ds_read_b64_tr_b16 v[82:83], v133 offset:17536
	s_nop 1
	ds_read_b64_tr_b16 v[84:85], v133 offset:21888
	s_waitcnt lgkmcnt(3)
	v_mfma_f32_16x16x32_bf16 v[78:81], v[144:147], v[62:65], v[88:91]
	s_waitcnt lgkmcnt(2)
	v_mfma_f32_16x16x32_bf16 v[86:89], v[148:151], v[62:65], v[92:95]
	s_nop 2
	ds_read_b64_tr_b16 v[92:93], v133 offset:21920
	ds_read_b64_tr_b16 v[90:91], v133 offset:17568
	ds_read_b64_tr_b16 v[144:145], v133 offset:17600
	ds_read_b64_tr_b16 v[148:149], v133 offset:17632
	ds_read_b64_tr_b16 v[146:147], v133 offset:21952
	ds_read_b64_tr_b16 v[150:151], v133 offset:21984
	s_waitcnt lgkmcnt(6)
	v_mfma_f32_16x16x32_bf16 v[82:85], v[82:85], v[62:65], v[96:99]
	s_waitcnt lgkmcnt(4)
	v_mfma_f32_16x16x32_bf16 v[90:93], v[90:93], v[62:65], v[100:103]
	s_waitcnt lgkmcnt(1)
	v_mfma_f32_16x16x32_bf16 v[94:97], v[144:147], v[62:65], v[140:143]
	s_waitcnt lgkmcnt(0)
	v_mfma_f32_16x16x32_bf16 v[62:65], v[148:151], v[62:65], v[70:73]
	v_mul_f32_e64 v58, v58, v8
	v_mul_f32_e64 v59, v59, v8
	v_pk_mul_f32 v[54:55], v[54:55], v[8:9] op_sel_hi:[1,0]
	v_pk_mul_f32 v[70:71], v[60:61], v[8:9] op_sel_hi:[1,0]
	v_pk_mul_f32 v[56:57], v[56:57], v[8:9] op_sel_hi:[1,0]
	v_cvt_pk_bf16_f32 v54, v54, v55
	v_cvt_pk_bf16_f32 v55, v58, v59
	ds_read_b64_tr_b16 v[60:61], v133 offset:30464
	ds_read_b64_tr_b16 v[58:59], v133 offset:26112
	v_cvt_pk_bf16_f32 v56, v56, v57
	v_cvt_pk_bf16_f32 v57, v70, v71
	ds_read_b64_tr_b16 v[72:73], v133 offset:30496
	ds_read_b64_tr_b16 v[70:71], v133 offset:26144
	ds_read_b64_tr_b16 v[98:99], v133 offset:26176
	ds_read_b64_tr_b16 v[102:103], v133 offset:26208
	ds_read_b64_tr_b16 v[100:101], v133 offset:30528
	ds_read_b64_tr_b16 v[104:105], v133 offset:30560
	s_waitcnt lgkmcnt(6)
	v_mfma_f32_16x16x32_bf16 v[58:61], v[58:61], v[54:57], v[66:69]
	s_waitcnt lgkmcnt(4)
	v_mfma_f32_16x16x32_bf16 v[66:69], v[70:73], v[54:57], v[74:77]
	s_nop 2
	ds_read_b64_tr_b16 v[74:75], v133 offset:26240
	ds_read_b64_tr_b16 v[76:77], v133 offset:30592
	s_waitcnt lgkmcnt(3)
	v_mfma_f32_16x16x32_bf16 v[70:73], v[98:101], v[54:57], v[78:81]
	s_waitcnt lgkmcnt(2)
	v_mfma_f32_16x16x32_bf16 v[78:81], v[102:105], v[54:57], v[86:89]
	s_nop 2
	ds_read_b64_tr_b16 v[88:89], v133 offset:30624
	ds_read_b64_tr_b16 v[86:87], v133 offset:26272
	ds_read_b64_tr_b16 v[98:99], v133 offset:26304
	ds_read_b64_tr_b16 v[102:103], v133 offset:26336
	ds_read_b64_tr_b16 v[100:101], v133 offset:30656
	ds_read_b64_tr_b16 v[104:105], v133 offset:30688
	s_waitcnt lgkmcnt(6)
	v_mfma_f32_16x16x32_bf16 v[74:77], v[74:77], v[54:57], v[82:85]
	s_waitcnt lgkmcnt(4)
	v_mfma_f32_16x16x32_bf16 v[82:85], v[86:89], v[54:57], v[90:93]
	s_waitcnt lgkmcnt(1)
	v_mfma_f32_16x16x32_bf16 v[86:89], v[98:101], v[54:57], v[94:97]
	s_waitcnt lgkmcnt(0)
	v_mfma_f32_16x16x32_bf16 v[54:57], v[102:105], v[54:57], v[62:65]
	v_mul_f32_e64 v36, v36, v8
	v_mul_f32_e64 v37, v37, v8
	v_pk_mul_f32 v[32:33], v[32:33], v[8:9] op_sel_hi:[1,0]
	v_pk_mul_f32 v[62:63], v[38:39], v[8:9] op_sel_hi:[1,0]
	v_pk_mul_f32 v[34:35], v[34:35], v[8:9] op_sel_hi:[1,0]
	v_cvt_pk_bf16_f32 v32, v32, v33
	v_cvt_pk_bf16_f32 v33, v36, v37
	ds_read_b64_tr_b16 v[38:39], v133 offset:39168
	ds_read_b64_tr_b16 v[36:37], v133 offset:34816
	v_cvt_pk_bf16_f32 v34, v34, v35
	v_cvt_pk_bf16_f32 v35, v62, v63
	ds_read_b64_tr_b16 v[64:65], v133 offset:39200
	ds_read_b64_tr_b16 v[62:63], v133 offset:34848
	ds_read_b64_tr_b16 v[90:91], v133 offset:34880
	ds_read_b64_tr_b16 v[94:95], v133 offset:34912
	ds_read_b64_tr_b16 v[92:93], v133 offset:39232
	ds_read_b64_tr_b16 v[96:97], v133 offset:39264
	s_waitcnt lgkmcnt(6)
	v_mfma_f32_16x16x32_bf16 v[36:39], v[36:39], v[32:35], v[58:61]
	s_waitcnt lgkmcnt(4)
	v_mfma_f32_16x16x32_bf16 v[58:61], v[62:65], v[32:35], v[66:69]
	s_nop 2
	ds_read_b64_tr_b16 v[66:67], v133 offset:34944
	ds_read_b64_tr_b16 v[68:69], v133 offset:39296
	s_waitcnt lgkmcnt(3)
	v_mfma_f32_16x16x32_bf16 v[62:65], v[90:93], v[32:35], v[70:73]
	s_waitcnt lgkmcnt(2)
	v_mfma_f32_16x16x32_bf16 v[70:73], v[94:97], v[32:35], v[78:81]
	s_nop 2
	ds_read_b64_tr_b16 v[80:81], v133 offset:39328
	ds_read_b64_tr_b16 v[78:79], v133 offset:34976
	ds_read_b64_tr_b16 v[90:91], v133 offset:35008
	ds_read_b64_tr_b16 v[94:95], v133 offset:35040
	ds_read_b64_tr_b16 v[92:93], v133 offset:39360
	ds_read_b64_tr_b16 v[96:97], v133 offset:39392
	s_waitcnt lgkmcnt(6)
	v_mfma_f32_16x16x32_bf16 v[66:69], v[66:69], v[32:35], v[74:77]
	s_waitcnt lgkmcnt(4)
	v_mfma_f32_16x16x32_bf16 v[74:77], v[78:81], v[32:35], v[82:85]
	s_waitcnt lgkmcnt(1)
	v_mfma_f32_16x16x32_bf16 v[78:81], v[90:93], v[32:35], v[86:89]
	s_waitcnt lgkmcnt(0)
	v_mfma_f32_16x16x32_bf16 v[32:35], v[94:97], v[32:35], v[54:57]
	v_mul_f32_e64 v28, v28, v8
	v_mul_f32_e64 v29, v29, v8
	v_pk_mul_f32 v[24:25], v[24:25], v[8:9] op_sel_hi:[1,0]
	v_pk_mul_f32 v[54:55], v[30:31], v[8:9] op_sel_hi:[1,0]
	v_pk_mul_f32 v[26:27], v[26:27], v[8:9] op_sel_hi:[1,0]
	v_cvt_pk_bf16_f32 v24, v24, v25
	v_cvt_pk_bf16_f32 v25, v28, v29
	ds_read_b64_tr_b16 v[30:31], v133 offset:47872
	ds_read_b64_tr_b16 v[28:29], v133 offset:43520
	v_cvt_pk_bf16_f32 v26, v26, v27
	v_cvt_pk_bf16_f32 v27, v54, v55
	ds_read_b64_tr_b16 v[56:57], v133 offset:47904
	ds_read_b64_tr_b16 v[54:55], v133 offset:43552
	ds_read_b64_tr_b16 v[82:83], v133 offset:43584
	ds_read_b64_tr_b16 v[86:87], v133 offset:43616
	ds_read_b64_tr_b16 v[84:85], v133 offset:47936
	ds_read_b64_tr_b16 v[88:89], v133 offset:47968
	s_waitcnt lgkmcnt(6)
	v_mfma_f32_16x16x32_bf16 v[28:31], v[28:31], v[24:27], v[36:39]
	s_waitcnt lgkmcnt(4)
	v_mfma_f32_16x16x32_bf16 v[36:39], v[54:57], v[24:27], v[58:61]
	s_nop 2
	ds_read_b64_tr_b16 v[58:59], v133 offset:43648
	ds_read_b64_tr_b16 v[60:61], v133 offset:48000
	s_waitcnt lgkmcnt(3)
	v_mfma_f32_16x16x32_bf16 v[54:57], v[82:85], v[24:27], v[62:65]
	s_waitcnt lgkmcnt(2)
	v_mfma_f32_16x16x32_bf16 v[62:65], v[86:89], v[24:27], v[70:73]
	s_nop 2
	ds_read_b64_tr_b16 v[72:73], v133 offset:48032
	ds_read_b64_tr_b16 v[70:71], v133 offset:43680
	ds_read_b64_tr_b16 v[82:83], v133 offset:43712
	ds_read_b64_tr_b16 v[86:87], v133 offset:43744
	ds_read_b64_tr_b16 v[84:85], v133 offset:48064
	ds_read_b64_tr_b16 v[88:89], v133 offset:48096
	s_waitcnt lgkmcnt(6)
	v_mfma_f32_16x16x32_bf16 v[58:61], v[58:61], v[24:27], v[66:69]
	s_waitcnt lgkmcnt(4)
	v_mfma_f32_16x16x32_bf16 v[66:69], v[70:73], v[24:27], v[74:77]
	s_waitcnt lgkmcnt(1)
	v_mfma_f32_16x16x32_bf16 v[70:73], v[82:85], v[24:27], v[78:81]
	s_waitcnt lgkmcnt(0)
	v_mfma_f32_16x16x32_bf16 v[24:27], v[86:89], v[24:27], v[32:35]
	s_nop 2
	ds_read_b64_tr_b16 v[34:35], v133 offset:56576
	ds_read_b64_tr_b16 v[32:33], v133 offset:52224
	ds_read_b64_tr_b16 v[76:77], v133 offset:56608
	ds_read_b64_tr_b16 v[74:75], v133 offset:52256
	ds_read_b64_tr_b16 v[78:79], v133 offset:52288
	ds_read_b64_tr_b16 v[82:83], v133 offset:52320
	ds_read_b64_tr_b16 v[80:81], v133 offset:56640
	ds_read_b64_tr_b16 v[84:85], v133 offset:56672
	v_pk_mul_f32 v[14:15], v[14:15], v[8:9] op_sel_hi:[1,0]
	v_pk_mul_f32 v[10:11], v[10:11], v[8:9] op_sel_hi:[1,0]
	v_pk_mul_f32 v[22:23], v[22:23], v[8:9] op_sel_hi:[1,0]
	v_pk_mul_f32 v[12:13], v[12:13], v[8:9] op_sel_hi:[1,0]
	v_cvt_pk_bf16_f32 v10, v10, v11
	v_cvt_pk_bf16_f32 v11, v14, v15
	v_cvt_pk_bf16_f32 v12, v12, v13
	v_cvt_pk_bf16_f32 v13, v22, v23
	s_waitcnt lgkmcnt(6)
	s_nop 0
	v_mfma_f32_16x16x32_bf16 v[28:31], v[32:35], v[10:13], v[28:31]
	s_waitcnt lgkmcnt(4)
	v_mfma_f32_16x16x32_bf16 v[32:35], v[74:77], v[10:13], v[36:39]
	s_waitcnt lgkmcnt(1)
	v_mfma_f32_16x16x32_bf16 v[36:39], v[78:81], v[10:13], v[54:57]
	s_nop 2
	ds_read_b64_tr_b16 v[54:55], v133 offset:52352
	ds_read_b64_tr_b16 v[56:57], v133 offset:56704
	s_waitcnt lgkmcnt(2)
	v_mfma_f32_16x16x32_bf16 v[62:65], v[82:85], v[10:13], v[62:65]
	ds_read_b64_tr_b16 v[76:77], v133 offset:56736
	ds_read_b64_tr_b16 v[74:75], v133 offset:52384
	ds_read_b64_tr_b16 v[78:79], v133 offset:52416
	ds_read_b64_tr_b16 v[82:83], v133 offset:52448
	ds_read_b64_tr_b16 v[80:81], v133 offset:56768
	ds_read_b64_tr_b16 v[84:85], v133 offset:56800
	s_waitcnt lgkmcnt(6)
	v_mfma_f32_16x16x32_bf16 v[54:57], v[54:57], v[10:13], v[58:61]
	s_waitcnt lgkmcnt(4)
	v_mfma_f32_16x16x32_bf16 v[58:61], v[74:77], v[10:13], v[66:69]
	s_waitcnt lgkmcnt(1)
	v_mfma_f32_16x16x32_bf16 v[66:69], v[78:81], v[10:13], v[70:73]
	s_waitcnt lgkmcnt(0)
	v_mfma_f32_16x16x32_bf16 v[10:13], v[82:85], v[10:13], v[24:27]
	v_mul_f32_e64 v4, v4, v8
	v_mul_f32_e64 v5, v5, v8
	v_pk_mul_f32 v[0:1], v[0:1], v[8:9] op_sel_hi:[1,0]
	v_pk_mul_f32 v[14:15], v[6:7], v[8:9] op_sel_hi:[1,0]
	v_cvt_pk_bf16_f32 v0, v0, v1
	v_cvt_pk_bf16_f32 v1, v4, v5
	ds_read_b64_tr_b16 v[6:7], v133 offset:65280
	ds_read_b64_tr_b16 v[4:5], v133 offset:60928
	ds_read_b64_tr_b16 v[24:25], v133 offset:65312
	ds_read_b64_tr_b16 v[22:23], v133 offset:60960
	ds_read_b64_tr_b16 v[70:71], v133 offset:60992
	ds_read_b64_tr_b16 v[74:75], v133 offset:61024
	ds_read_b64_tr_b16 v[72:73], v133 offset:65344
	ds_read_b64_tr_b16 v[76:77], v133 offset:65376
	v_pk_mul_f32 v[2:3], v[2:3], v[8:9] op_sel_hi:[1,0]
	s_nop 0
	v_cvt_pk_bf16_f32 v2, v2, v3
	v_cvt_pk_bf16_f32 v3, v14, v15
	s_waitcnt lgkmcnt(6)
	s_nop 0
	v_mfma_f32_16x16x32_bf16 v[4:7], v[4:7], v[0:3], v[28:31]
	s_waitcnt lgkmcnt(4)
	v_mfma_f32_16x16x32_bf16 v[22:25], v[22:25], v[0:3], v[32:35]
	s_nop 0
	ds_read_b64_tr_b16 v[30:31], v133 offset:61056
	s_nop 0
	ds_read_b64_tr_b16 v[32:33], v133 offset:65408
	s_waitcnt lgkmcnt(3)
	v_mfma_f32_16x16x32_bf16 v[26:29], v[70:73], v[0:3], v[36:39]
	s_waitcnt lgkmcnt(2)
	v_mfma_f32_16x16x32_bf16 v[34:37], v[74:77], v[0:3], v[62:65]
	s_nop 2
	ds_read_b64_tr_b16 v[64:65], v133 offset:65440
	ds_read_b64_tr_b16 v[62:63], v133 offset:61088
	ds_read_b64_tr_b16 v[70:71], v133 offset:61120
	ds_read_b64_tr_b16 v[74:75], v133 offset:61152
	ds_read_b64_tr_b16 v[72:73], v133 offset:65472
	ds_read_b64_tr_b16 v[76:77], v133 offset:65504
	s_waitcnt lgkmcnt(6)
	v_mfma_f32_16x16x32_bf16 v[30:33], v[30:33], v[0:3], v[54:57]
	s_waitcnt lgkmcnt(4)
	v_mfma_f32_16x16x32_bf16 v[54:57], v[62:65], v[0:3], v[58:61]
	s_waitcnt lgkmcnt(1)
	v_mfma_f32_16x16x32_bf16 v[58:61], v[70:73], v[0:3], v[66:69]
	s_waitcnt lgkmcnt(0)
	v_mfma_f32_16x16x32_bf16 v[0:3], v[74:77], v[0:3], v[10:13]
	s_add_i32 s2, s2, -1
	v_lshl_add_u64 v[8:9], s[22:23], 0, v[18:19]
	v_cvt_pk_bf16_f32 v4, v4, v5
	v_cvt_pk_bf16_f32 v5, v6, v7
	s_nop 3
	v_cvt_pk_bf16_f32 v0, v0, v1
	v_cvt_pk_bf16_f32 v1, v2, v3
	v_lshl_add_u64 v[16:17], v[16:17], 0, s[18:19]
	v_lshl_add_u64 v[18:19], v[18:19], 0, s[24:25]
	v_lshl_add_u64 v[20:21], v[20:21], 0, s[24:25]
	s_cmp_eq_u32 s2, 0
	v_cvt_pk_bf16_f32 v6, v22, v23
	v_cvt_pk_bf16_f32 v7, v24, v25
	v_cvt_pk_bf16_f32 v10, v26, v27
	v_cvt_pk_bf16_f32 v11, v28, v29
	v_cvt_pk_bf16_f32 v12, v34, v35
	v_cvt_pk_bf16_f32 v13, v36, v37
	v_cvt_pk_bf16_f32 v14, v30, v31
	v_cvt_pk_bf16_f32 v15, v32, v33
	v_cvt_pk_bf16_f32 v22, v54, v55
	v_cvt_pk_bf16_f32 v23, v56, v57
	v_cvt_pk_bf16_f32 v24, v58, v59
	v_cvt_pk_bf16_f32 v25, v60, v61
	global_store_dwordx2 v[8:9], v[4:5], off offset:-128
	global_store_dwordx2 v[8:9], v[6:7], off offset:-96
	global_store_dwordx2 v[8:9], v[10:11], off offset:-64
	global_store_dwordx2 v[8:9], v[12:13], off offset:-32
	global_store_dwordx2 v[8:9], v[14:15], off
	global_store_dwordx2 v[8:9], v[22:23], off offset:32
	global_store_dwordx2 v[8:9], v[24:25], off offset:64
	global_store_dwordx2 v[8:9], v[0:1], off offset:96
	s_cbranch_scc0 .LBB0_1059
	s_branch .LBB0_1051
